# attention unit epilogue: per-layer lambda scalar computed once per wave and kept in an SGPR (4 loads + 12 shuffles per unit skipped afterwards)
# speedup vs baseline: 1.0261x; 1.0086x over previous
; __device__ __forceinline__ int fresh_tid(int wave_s) { unsigned m = ~0u; asm volatile("" : "+s"(m)); int t = wave_s * 64 + (int)__builtin_amdgcn_mbcnt_hi(m, __builtin_amdgcn_mbcnt_lo(m, 0u)); asm volatile("" : "+v"(t)); return t; }
; __device__ __forceinline__ unsigned xb_ld(unsigned* p)              { return __hip_atomic_load(p, __ATOMIC_RELAXED, __HIP_MEMORY_SCOPE_AGENT); }
; __device__ __forceinline__ void xcd_barrier_complete(unsigned* bar, unsigned x, unsigned& nloc, unsigned& nx) {
;     const unsigned G = gridDim.x * gridDim.y * gridDim.z;
;     unsigned sum, cnt, mine, sp = 0u;
;     for (;;) {
;         sum = 0u; cnt = 0u; mine = 0u;
; #pragma unroll
;         for (unsigned j = 0; j < 16; ++j) { const unsigned c = xb_ld(&bar[XB_XCNT(j)]); sum += c; cnt += (c > 0u) ? 1u : 0u; mine = (j == x) ? c : mine; }
; __device__ __forceinline__ void xcd_barrier(const XcdBarrier& b) {
;     asm volatile("s_waitcnt vmcnt(0)" ::: "memory");
;     __syncthreads();
;     if (fresh_tid(b.wave_s) == 0) {
;         unsigned* bar = b.bar;
;         __builtin_amdgcn_s_waitcnt(0);
;         unsigned nloc = b.st[0], nx = b.st[1];
;         if (nloc == 0u) { xcd_barrier_complete(bar, b.x, nloc, nx); b.st[0] = nloc; b.st[1] = nx; }
.Lp0b_skip:
	s_mov_b32 s32, -1
	s_mov_b32 s0, -1
	s_waitcnt vmcnt(0)
	s_waitcnt vmcnt(0)
	s_barrier
	s_nop 0
	v_mbcnt_lo_u32_b32 v0, s0, 0
	v_mbcnt_hi_u32_b32 v0, s0, v0
	v_add_u32_e32 v0, s33, v0
	s_nop 0
	v_cmp_eq_u32_e32 vcc, 0, v0
	s_and_saveexec_b64 s[0:1], vcc
	s_cbranch_execz .LBB0_655
	s_add_i32 s2, 0, 0x23020
	v_mov_b32_e32 v0, s2
	s_waitcnt vmcnt(0) expcnt(0) lgkmcnt(0)
	ds_read_b32 v2, v0
	s_add_i32 s2, 0, 0x23024
	v_mov_b32_e32 v0, s2
	ds_read_b32 v0, v0
	s_waitcnt lgkmcnt(1)
	v_cmp_ne_u32_e32 vcc, 0, v2
	s_cbranch_vccnz .LBB0_619
	v_readlane_b32 s2, v255, 0
	v_readlane_b32 s3, v255, 1
	s_load_dwordx2 s[6:7], s[2:3], 0x4
	s_add_u32 s2, s34, 0x1000
	s_addc_u32 s3, s35, 0
	s_add_u32 s4, s34, 0x1100
	s_addc_u32 s5, s35, 0
	s_waitcnt lgkmcnt(0)
	s_mul_i32 s30, s6, s15
	s_add_u32 s6, s34, 0x1200
	s_mul_i32 s30, s30, s7
	s_addc_u32 s7, s35, 0
	s_add_u32 s8, s34, 0x1300
	s_addc_u32 s9, s35, 0
	s_mov_b32 s31, 1
	v_mov_b32_e32 v16, 0
	s_branch .LBB0_607

; #define LAS __attribute__((address_space(3)))
; __device__ __forceinline__ int fresh_tid(int wave_s) { unsigned m = ~0u; asm volatile("" : "+s"(m)); int t = wave_s * 64 + (int)__builtin_amdgcn_mbcnt_hi(m, __builtin_amdgcn_mbcnt_lo(m, 0u)); asm volatile("" : "+v"(t)); return t; }
; template <bool SAMPLE> __device__ __forceinline__ void attn_unit16(const Ctx& c, LAS unsigned char* lds, int b, int h, int qb, int wave_s) {
;     ...
;     const int lane2 = fresh_tid(wave_s) & 63, c16b = lane2 & 15, q4b = lane2 >> 4;
;     LAS float* X = (LAS float*)lds;
;     if (active) {
;         float lam;
;         { const float a = c.lq1[lane2] * c.lk1[lane2], bb = c.lq2[lane2] * c.lk2[lane2]; lam = __expf(wave_sum(a)) - __expf(wave_sum(bb)) + 0.2f; }
.LBB0_884:
	s_mov_b32 s0, -1
	v_and_b32_e32 v215, 64, v212
	v_mbcnt_lo_u32_b32 v0, s0, 0
	v_mbcnt_hi_u32_b32 v0, s0, v0
	s_waitcnt vmcnt(1)
	v_add_u32_e32 v7, s33, v0
	v_xor_b32_e32 v5, 1, v212
	v_and_b32_e32 v6, 63, v7
	v_lshlrev_b32_e32 v0, 2, v6
	s_cmp_eq_u32 s32, -1
	s_cbranch_scc0 .Lq1_lam_skipld
	global_load_dword v2, v0, s[18:19]
	global_load_dword v3, v0, s[20:21]
	global_load_dword v4, v0, s[22:23]
	s_nop 0
	global_load_dword v0, v0, s[24:25]
	s_waitcnt vmcnt(4)
	s_branch .Lq1_lam_ld_done

; template <bool SAMPLE> __device__ __forceinline__ void attn_unit16(const Ctx& c, LAS unsigned char* lds, int b, int h, int qb, int wave_s) {
;     ...
;         { const float a = c.lq1[lane2] * c.lk1[lane2], bb = c.lq2[lane2] * c.lk2[lane2]; lam = __expf(wave_sum(a)) - __expf(wave_sum(bb)) + 0.2f; }
; #pragma unroll
;         for (int qt = 0; qt < NQT; ++qt) { float l = ls[qt] + __shfl_xor(ls[qt], 16); l += __shfl_xor(l, 32);
;             const float inv = (mp ? lam : 1.f) / l;
.Lq1_lam_ld_done:
	v_add_u32_e32 v13, 64, v215
	v_cmp_lt_i32_e32 vcc, v5, v13
	v_xor_b32_e32 v8, 2, v212
	v_xor_b32_e32 v9, 4, v212
	v_cndmask_b32_e32 v5, v212, v5, vcc
	v_lshlrev_b32_e32 v210, 2, v5
	v_cmp_lt_i32_e32 vcc, v8, v13
	v_xor_b32_e32 v10, 8, v212
	v_xor_b32_e32 v11, 16, v212
	v_cndmask_b32_e32 v8, v212, v8, vcc
	v_lshlrev_b32_e32 v211, 2, v8
	v_cmp_lt_i32_e32 vcc, v9, v13
	v_xor_b32_e32 v12, 32, v212
	s_cmp_eq_u32 s81, 0
	v_cndmask_b32_e32 v9, v212, v9, vcc
	v_lshlrev_b32_e32 v214, 2, v9
	v_cmp_lt_i32_e32 vcc, v10, v13
	s_cselect_b64 s[2:3], -1, 0
	v_lshrrev_b32_e32 v9, 2, v7
	v_cndmask_b32_e32 v10, v212, v10, vcc
	v_cmp_lt_i32_e32 vcc, v11, v13
	v_lshlrev_b32_e32 v213, 2, v10
	s_cmp_lg_u32 s81, 0
	v_cndmask_b32_e32 v11, v212, v11, vcc
	v_cmp_lt_i32_e32 vcc, v12, v13
	v_lshlrev_b32_e32 v217, 2, v11
	ds_bpermute_b32 v8, v217, v199
	s_waitcnt lgkmcnt(0)
	v_add_f32_e32 v8, v199, v8
	s_cmp_eq_u32 s32, -1
	s_cbranch_scc0 .Lq1_lam_cached
	s_waitcnt vmcnt(2)
	v_mul_f32_e32 v5, v2, v3
	ds_bpermute_b32 v5, v210, v5
	s_waitcnt vmcnt(0)
	v_mul_f32_e32 v14, v4, v0
	ds_bpermute_b32 v14, v210, v14
	s_waitcnt lgkmcnt(1)
	v_fmac_f32_e32 v5, v2, v3
	v_cndmask_b32_e32 v3, v212, v12, vcc
	s_waitcnt lgkmcnt(0)
	v_fmac_f32_e32 v14, v4, v0
	ds_bpermute_b32 v0, v211, v5
	ds_bpermute_b32 v2, v211, v14
	v_lshlrev_b32_e32 v216, 2, v3
	ds_bpermute_b32 v12, v216, v8
	s_waitcnt lgkmcnt(2)
	v_add_f32_e32 v0, v5, v0
	s_waitcnt lgkmcnt(1)
	v_add_f32_e32 v2, v14, v2
	ds_bpermute_b32 v4, v214, v0
	ds_bpermute_b32 v5, v214, v2
	s_waitcnt lgkmcnt(1)
	v_add_f32_e32 v0, v0, v4
	s_waitcnt lgkmcnt(0)
	v_add_f32_e32 v2, v2, v5
	ds_bpermute_b32 v3, v213, v0
	ds_bpermute_b32 v4, v213, v2
	ds_bpermute_b32 v5, v217, v198
	s_waitcnt lgkmcnt(2)
	v_add_f32_e32 v0, v0, v3
	s_waitcnt lgkmcnt(1)
	v_add_f32_e32 v2, v2, v4
	ds_bpermute_b32 v3, v217, v0
	ds_bpermute_b32 v10, v217, v2
	s_waitcnt lgkmcnt(2)
	v_add_f32_e32 v5, v198, v5
	ds_bpermute_b32 v11, v216, v5
	v_and_b32_e32 v4, 12, v9
	s_waitcnt lgkmcnt(2)
	v_add_f32_e32 v0, v0, v3
	s_waitcnt lgkmcnt(1)
	v_add_f32_e32 v2, v2, v10
	ds_bpermute_b32 v3, v216, v0
	ds_bpermute_b32 v10, v216, v2
	v_or_b32_e32 v9, v215, v4
	v_lshlrev_b32_e32 v9, 2, v9
	s_waitcnt lgkmcnt(1)
	v_add_f32_e32 v0, v0, v3
	s_waitcnt lgkmcnt(0)
	v_add_f32_e32 v2, v2, v10
	v_mul_f32_e32 v0, 0x3fb8aa3b, v0
	v_mul_f32_e32 v2, 0x3fb8aa3b, v2
	v_exp_f32_e32 v0, v0
	v_exp_f32_e32 v2, v2
	v_add_f32_e32 v3, v5, v11
	v_add_f32_e32 v5, v8, v12
	v_sub_f32_e32 v0, v0, v2
	v_add_f32_e32 v0, 0x3e4ccccd, v0
	s_nop 0
	v_readfirstlane_b32 s32, v0
	s_branch .Lq1_lam_join
.Lq1_lam_cached:
	v_cndmask_b32_e32 v3, v212, v12, vcc
	v_lshlrev_b32_e32 v216, 2, v3
	ds_bpermute_b32 v12, v216, v8
	ds_bpermute_b32 v5, v217, v198
	v_and_b32_e32 v4, 12, v9
	s_waitcnt lgkmcnt(0)
	v_add_f32_e32 v5, v198, v5
	ds_bpermute_b32 v11, v216, v5
	v_or_b32_e32 v9, v215, v4
	v_lshlrev_b32_e32 v9, 2, v9
	s_waitcnt lgkmcnt(0)
	v_add_f32_e32 v3, v5, v11
	v_add_f32_e32 v5, v8, v12
	v_mov_b32_e32 v0, s32
; template <bool SAMPLE> __device__ __forceinline__ void attn_unit16(const Ctx& c, LAS unsigned char* lds, int b, int h, int qb, int wave_s) {
;     ...
; #pragma unroll
;         for (int qt = 0; qt < NQT; ++qt) { float l = ls[qt] + __shfl_xor(ls[qt], 16); l += __shfl_xor(l, 32);
;             const float inv = (mp ? lam : 1.f) / l;
; #pragma unroll
;             for (int i = 0; i < 4; ++i) { const float fi = __shfl(inv, 4 * q4b + i);
; #pragma unroll
;                 for (int et = 0; et < 8; ++et) o[qt][et][i] *= fi; } }
;         if (mp) {
; #pragma unroll
;             for (int qt = 0; qt < NQT; ++qt)
; #pragma unroll
;                 for (int et = 0; et < 8; ++et)
; #pragma unroll
;                     for (int i = 0; i < 4; ++i) X[(g * 64 + qt * 32 + et * 4 + i) * 64 + lane2] = o[qt][et][i];
;         }
.Lq1_lam_join:
	s_cmp_lg_u32 s81, 0
	v_cndmask_b32_e64 v0, v0, 1.0, s[2:3]
	v_div_scale_f32 v2, s[0:1], v3, v3, v0
	v_rcp_f32_e32 v11, v2
	v_div_scale_f32 v10, s[0:1], v5, v5, v0
	v_rcp_f32_e32 v12, v10
	v_fma_f32 v14, -v2, v11, 1.0
	v_div_scale_f32 v8, vcc, v0, v3, v0
	v_fmac_f32_e32 v11, v14, v11
	v_fma_f32 v15, -v10, v12, 1.0
	v_mul_f32_e32 v14, v8, v11
	v_div_scale_f32 v13, s[0:1], v0, v5, v0
	v_fmac_f32_e32 v12, v15, v12
	v_fma_f32 v16, -v2, v14, v8
	v_mul_f32_e32 v15, v13, v12
	v_fmac_f32_e32 v14, v16, v11
	v_fma_f32 v17, -v10, v15, v13
	v_fma_f32 v2, -v2, v14, v8
	v_fmac_f32_e32 v15, v17, v12
	v_div_fmas_f32 v2, v2, v11, v14
	v_fma_f32 v8, -v10, v15, v13
	v_div_fixup_f32 v2, v2, v3, v0
	s_mov_b64 vcc, s[0:1]
	v_div_fmas_f32 v3, v8, v12, v15
	ds_bpermute_b32 v8, v9, v2
	v_div_fixup_f32 v13, v3, v5, v0
	ds_bpermute_b32 v10, v9, v2 offset:4
	ds_bpermute_b32 v11, v9, v2 offset:8
	ds_bpermute_b32 v12, v9, v2 offset:12
	ds_bpermute_b32 v16, v9, v13
	s_waitcnt lgkmcnt(4)
	v_mul_f32_e32 v14, v128, v8
	v_mul_f32_e32 v15, v124, v8
	v_mul_f32_e32 v19, v116, v8
	v_mul_f32_e32 v18, v104, v8
	v_mul_f32_e32 v5, v88, v8
	v_mul_f32_e32 v3, v80, v8
	v_mul_f32_e32 v2, v68, v8
	v_mul_f32_e32 v0, v56, v8
	ds_bpermute_b32 v8, v9, v13 offset:4
	s_waitcnt lgkmcnt(4)
	v_mul_f32_e32 v113, v129, v10
	v_mul_f32_e32 v114, v125, v10
	v_mul_f32_e32 v112, v117, v10
	v_mul_f32_e32 v105, v105, v10
	v_mul_f32_e32 v104, v89, v10
	v_mul_f32_e32 v95, v81, v10
	v_mul_f32_e32 v94, v69, v10
	v_mul_f32_e32 v93, v57, v10
	s_waitcnt lgkmcnt(3)
	v_mul_f32_e32 v85, v82, v11
	v_mul_f32_e32 v82, v58, v11
	s_waitcnt lgkmcnt(2)
	v_mul_f32_e32 v69, v59, v12
	s_waitcnt lgkmcnt(1)
	v_mul_f32_e32 v59, v52, v16
	v_mul_f32_e32 v58, v48, v16
	s_waitcnt lgkmcnt(0)
	v_mul_f32_e32 v48, v121, v8
	v_mul_f32_e32 v52, v109, v8
	v_mul_f32_e32 v45, v101, v8
	v_mul_f32_e32 v44, v97, v8
	ds_bpermute_b32 v10, v9, v13 offset:8
	v_mul_f32_e32 v57, v77, v8
	v_mul_f32_e32 v56, v65, v8
	v_mul_f32_e32 v47, v53, v8
	v_mul_f32_e32 v46, v49, v8
	ds_bpermute_b32 v8, v9, v13 offset:12
	v_mul_f32_e32 v89, v130, v11
	v_mul_f32_e32 v92, v126, v11
	v_mul_f32_e32 v88, v118, v11
	v_mul_f32_e32 v87, v106, v11
	v_mul_f32_e32 v86, v90, v11
	v_mul_f32_e32 v84, v70, v11
	v_mul_f32_e32 v80, v131, v12
	v_mul_f32_e32 v81, v127, v12
	v_mul_f32_e32 v75, v119, v12
	v_mul_f32_e32 v74, v107, v12
	v_mul_f32_e32 v73, v91, v12
	v_mul_f32_e32 v72, v83, v12
	v_mul_f32_e32 v70, v71, v12
	v_mul_f32_e32 v63, v120, v16
	v_mul_f32_e32 v68, v108, v16
	v_mul_f32_e32 v61, v100, v16
	v_mul_f32_e32 v60, v96, v16
	v_mul_f32_e32 v27, v76, v16
	v_mul_f32_e32 v26, v64, v16
	s_waitcnt lgkmcnt(1)
	v_mul_f32_e32 v40, v122, v10
	v_mul_f32_e32 v41, v110, v10
	v_mul_f32_e32 v37, v102, v10
	v_mul_f32_e32 v36, v98, v10
	v_mul_f32_e32 v43, v78, v10
	v_mul_f32_e32 v42, v66, v10
	v_mul_f32_e32 v39, v54, v10
	v_mul_f32_e32 v38, v50, v10
	s_waitcnt lgkmcnt(0)
	v_mul_f32_e32 v34, v123, v8
	v_mul_f32_e32 v35, v111, v8
	v_mul_f32_e32 v33, v103, v8
	v_mul_f32_e32 v32, v99, v8
	v_mul_f32_e32 v31, v79, v8
	v_mul_f32_e32 v30, v67, v8
	v_mul_f32_e32 v29, v55, v8
	v_mul_f32_e32 v28, v51, v8
	s_cbranch_scc0 .LBB0_886
	s_lshl_b32 s0, s63, 14
	s_add_i32 s0, s0, 0
	v_lshl_add_u32 v8, v6, 2, s0
	ds_write2st64_b32 v8, v14, v113 offset1:1
	ds_write2st64_b32 v8, v89, v80 offset0:2 offset1:3
	ds_write2st64_b32 v8, v15, v114 offset0:4 offset1:5
	ds_write2st64_b32 v8, v92, v81 offset0:6 offset1:7
	ds_write2st64_b32 v8, v19, v112 offset0:8 offset1:9
	ds_write2st64_b32 v8, v88, v75 offset0:10 offset1:11
	ds_write2st64_b32 v8, v18, v105 offset0:12 offset1:13
	ds_write2st64_b32 v8, v87, v74 offset0:14 offset1:15
	ds_write2st64_b32 v8, v5, v104 offset0:16 offset1:17
	ds_write2st64_b32 v8, v86, v73 offset0:18 offset1:19
	ds_write2st64_b32 v8, v3, v95 offset0:20 offset1:21
	ds_write2st64_b32 v8, v85, v72 offset0:22 offset1:23
	ds_write2st64_b32 v8, v2, v94 offset0:24 offset1:25
	ds_write2st64_b32 v8, v84, v70 offset0:26 offset1:27
	ds_write2st64_b32 v8, v0, v93 offset0:28 offset1:29
	ds_write2st64_b32 v8, v82, v69 offset0:30 offset1:31
	ds_write2st64_b32 v8, v63, v48 offset0:32 offset1:33
	ds_write2st64_b32 v8, v40, v34 offset0:34 offset1:35
	ds_write2st64_b32 v8, v68, v52 offset0:36 offset1:37
	ds_write2st64_b32 v8, v41, v35 offset0:38 offset1:39
	ds_write2st64_b32 v8, v61, v45 offset0:40 offset1:41
	ds_write2st64_b32 v8, v37, v33 offset0:42 offset1:43
	ds_write2st64_b32 v8, v60, v44 offset0:44 offset1:45
	ds_write2st64_b32 v8, v36, v32 offset0:46 offset1:47
	ds_write2st64_b32 v8, v27, v57 offset0:48 offset1:49
	ds_write2st64_b32 v8, v43, v31 offset0:50 offset1:51
	ds_write2st64_b32 v8, v26, v56 offset0:52 offset1:53
	ds_write2st64_b32 v8, v42, v30 offset0:54 offset1:55
	ds_write2st64_b32 v8, v59, v47 offset0:56 offset1:57
	ds_write2st64_b32 v8, v39, v29 offset0:58 offset1:59
	ds_write2st64_b32 v8, v58, v46 offset0:60 offset1:61
	ds_write2st64_b32 v8, v38, v28 offset0:62 offset1:63
